# speedup vs baseline: 1.0035x; 1.0035x over previous
; __device__ __forceinline__ void attn_load_kv(KVRegs& R, const bf16* Z, const bf16* KC, const bf16* VC, const float* sinks, int idx, int kvh, int tid) {
;     const bool sample = idx >= 256; const int c = idx & 31; const int row0 = idx * 64;
;     const int jmin = sample ? 0 : (c >= 2 ? 0 : 2 - c);
;     const int kr = tid >> 3, d0 = (tid & 7) * 8;
;     const v4u z = {0u, 0u, 0u, 0u};
;     R.k0 = z; R.k1 = z; R.k2 = z; R.v0 = z; R.v1 = z; R.v2 = z;
;     if (sample) {
;         const size_t off = ((size_t)((idx - 256) * 128 + kr)) * 256 + kvh * 64 + d0;
;         R.k0 = *(const v4u*)(KC + off); R.v0 = *(const v4u*)(VC + off); R.k1 = *(const v4u*)(KC + off + 64 * 256); R.v1 = *(const v4u*)(VC + off + 64 * 256);
;     } else {
;         const bf16* zr = Z + (size_t)(row0 - 128 + kr) * DIN + kvh * 64 + d0;
;         if (jmin <= 0) { R.k0 = *(const v4u*)(zr + 2048); R.v0 = *(const v4u*)(zr + 2304); }
;         if (jmin <= 1) { R.k1 = *(const v4u*)(zr + (size_t)64 * DIN + 2048); R.v1 = *(const v4u*)(zr + (size_t)64 * DIN + 2304); }
;     }
;     { const bf16* zr = Z + (size_t)(row0 + kr) * DIN + kvh * 64 + d0; R.k2 = *(const v4u*)(zr + 2048); R.v2 = *(const v4u*)(zr + 2304); }
;     { const int wid = tid >> 6, lane = tid & 63, g = wid >> 1, qh = wid & 1, r = lane & 31, h = lane >> 5;
;       const bf16* qp = Z + (size_t)(row0 + qh * 32 + r) * DIN + 1024 + (kvh * 4 + g) * 64 + 8 * h;
;       R.q0 = *(const bf16x8*)qp; R.q1 = *(const bf16x8*)(qp + 16); R.q2 = *(const bf16x8*)(qp + 32); R.q3 = *(const bf16x8*)(qp + 48); R.sink = sinks[kvh * 4 + g]; }
; }
; __device__ __forceinline__ void attn_units(LAS unsigned char* lds, const bf16* Z, const bf16* KC, const bf16* VC, const float* sinks, bf16* MIXIN, int bx, int G, int tid, int wid, int lane) {
;     ...
;         f32x16 st[6];
;         {
;             bf16x8 ka[2][4];
; #pragma unroll
;             for (int s = 0; s < 4; ++s) ka[0][s] = *(const LAS bf16x8*)(Ks + r * ATT_KS + 16 * s + 8 * h);
;             __builtin_amdgcn_sched_barrier(0);
; #pragma unroll
;             for (int kt = 0; kt < 6; ++kt) {
;                 if (kt < 5) {
; #pragma unroll
;                     for (int s = 0; s < 4; ++s) ka[(kt + 1) & 1][s] = *(const LAS bf16x8*)(Ks + ((kt + 1) * 32 + r) * ATT_KS + 16 * s + 8 * h);
;                 }
;                 __builtin_amdgcn_sched_barrier(0);
; #pragma unroll
.LBB0_61:
	v_mov_b64_e32 v[6:7], s[8:9]
	v_mad_i64_i32 v[8:9], s[34:35], v9, s75, v[6:7]
	s_lshl_b32 s88, s13, 1
	v_lshl_add_u64 v[8:9], v[8:9], 0, s[88:89]
	v_mov_b32_e32 v151, v1
	v_lshl_add_u64 v[8:9], v[8:9], 0, v[150:151]
	v_add_co_u32_e32 v8, vcc, 0x1000, v8
	v_mov_b32_e32 v153, v1
	s_nop 0
	v_addc_co_u32_e32 v9, vcc, 0, v9, vcc
	global_load_dwordx4 v[114:117], v[8:9], off
	global_load_dwordx4 v[118:121], v[8:9], off offset:512
	v_or_b32_e32 v8, s12, v161
	v_mad_i64_i32 v[6:7], s[12:13], v8, s75, v[6:7]
	v_lshl_add_u32 v8, s4, 2, v160
	v_lshlrev_b32_e32 v10, 6, v8
	v_ashrrev_i32_e32 v11, 31, v10
	v_lshl_add_u64 v[6:7], v[10:11], 1, v[6:7]
	v_lshl_add_u64 v[6:7], v[6:7], 0, v[152:153]
	v_mov_b64_e32 v[246:247], v[6:7]
	v_ashrrev_i32_e32 v9, 31, v8
	v_lshl_add_u64 v[6:7], v[8:9], 2, s[28:29]
	global_load_dword v151, v[6:7], off
.LBB0_62:
	s_ashr_i32 s4, s5, 2
	s_cmpk_gt_i32 s4, 0xff
	ds_read_b128 v[6:9], v167
	ds_read_b128 v[10:13], v167 offset:32
	ds_read_b128 v[14:17], v167 offset:64
	ds_read_b128 v[18:21], v167 offset:96
	s_cselect_b64 s[12:13], -1, 0
	s_and_b32 s5, s4, 31
	s_cmp_gt_u32 s5, 1
	s_cselect_b64 s[34:35], -1, 0
	s_sub_i32 s5, 2, s5
	s_or_b64 s[12:13], s[12:13], s[34:35]
	s_and_b64 s[12:13], s[12:13], exec
	s_cselect_b32 s5, 0, s5
	ds_read_b128 v[22:25], v169
	ds_read_b128 v[26:29], v169 offset:32
	ds_read_b128 v[30:33], v169 offset:64
	ds_read_b128 v[34:37], v169 offset:96
	s_waitcnt lgkmcnt(7)
	v_mfma_f32_32x32x16_bf16 v[66:81], v[6:9], v[2:5], 0
	s_waitcnt lgkmcnt(6)
	v_mfma_f32_32x32x16_bf16 v[66:81], v[10:13], v[146:149], v[66:81]
	s_waitcnt lgkmcnt(5)
	v_mfma_f32_32x32x16_bf16 v[66:81], v[14:17], v[142:145], v[66:81]
	s_waitcnt lgkmcnt(4)
	v_mfma_f32_32x32x16_bf16 v[66:81], v[18:21], v[138:141], v[66:81]
	ds_read_b128 v[6:9], v170 offset:9216
	ds_read_b128 v[10:13], v170 offset:9248
	ds_read_b128 v[14:17], v170 offset:9280
	ds_read_b128 v[18:21], v170 offset:9312
	s_waitcnt lgkmcnt(7)
	v_mfma_f32_32x32x16_bf16 v[50:65], v[22:25], v[2:5], 0
	s_waitcnt lgkmcnt(6)
	v_mfma_f32_32x32x16_bf16 v[50:65], v[26:29], v[146:149], v[50:65]
	s_waitcnt lgkmcnt(5)
	v_mfma_f32_32x32x16_bf16 v[50:65], v[30:33], v[142:145], v[50:65]
	ds_read_b128 v[22:25], v171
	ds_read_b128 v[26:29], v171 offset:32
	ds_read_b128 v[30:33], v171 offset:64
	ds_read_b128 v[176:179], v171 offset:96
	s_waitcnt lgkmcnt(8)
	v_mfma_f32_32x32x16_bf16 v[50:65], v[34:37], v[138:141], v[50:65]
	s_waitcnt lgkmcnt(7)
	v_mfma_f32_32x32x16_bf16 v[34:49], v[6:9], v[2:5], 0
	s_waitcnt lgkmcnt(6)
	v_mfma_f32_32x32x16_bf16 v[34:49], v[10:13], v[146:149], v[34:49]
	s_waitcnt lgkmcnt(5)
	v_mfma_f32_32x32x16_bf16 v[34:49], v[14:17], v[142:145], v[34:49]
	ds_read_b128 v[6:9], v170 offset:18432
	ds_read_b128 v[10:13], v170 offset:18464
	ds_read_b128 v[14:17], v170 offset:18496
	ds_read_b128 v[182:185], v170 offset:18528
	s_waitcnt lgkmcnt(8)
	v_mfma_f32_32x32x16_bf16 v[34:49], v[18:21], v[138:141], v[34:49]
	s_waitcnt lgkmcnt(7)
	v_mfma_f32_32x32x16_bf16 v[82:97], v[22:25], v[2:5], 0
	s_waitcnt lgkmcnt(6)
	v_mfma_f32_32x32x16_bf16 v[82:97], v[26:29], v[146:149], v[82:97]
	s_waitcnt lgkmcnt(5)
	v_mfma_f32_32x32x16_bf16 v[82:97], v[30:33], v[142:145], v[82:97]
	s_waitcnt lgkmcnt(4)
	v_mfma_f32_32x32x16_bf16 v[82:97], v[176:179], v[138:141], v[82:97]
	ds_read_b128 v[176:179], v172
	ds_read_b128 v[186:189], v172 offset:32
	ds_read_b128 v[208:211], v172 offset:64
	ds_read_b128 v[212:215], v172 offset:96
	s_waitcnt lgkmcnt(7)
	v_mfma_f32_32x32x16_bf16 v[18:33], v[6:9], v[2:5], 0
	s_waitcnt lgkmcnt(6)
	v_mfma_f32_32x32x16_bf16 v[18:33], v[10:13], v[146:149], v[18:33]
	s_waitcnt lgkmcnt(5)
	v_mfma_f32_32x32x16_bf16 v[18:33], v[14:17], v[142:145], v[18:33]
	s_waitcnt lgkmcnt(4)
	v_mfma_f32_32x32x16_bf16 v[18:33], v[182:185], v[138:141], v[18:33]
	s_waitcnt lgkmcnt(3)
	v_mfma_f32_32x32x16_bf16 v[2:17], v[176:179], v[2:5], 0
	s_cmp_gt_i32 s5, 0
	v_mul_f32_e32 v153, 0x3fb8aa3b, v156
	s_cselect_b64 s[36:37], -1, 0
	s_cmp_lt_i32 s5, 1
	s_cselect_b64 s[34:35], -1, 0
	s_and_b64 vcc, exec, s[36:37]
	v_mov_b32_e32 v177, v153
	s_waitcnt lgkmcnt(2)
	v_mfma_f32_32x32x16_bf16 v[2:17], v[186:189], v[146:149], v[2:17]
	s_waitcnt lgkmcnt(1)
	v_mfma_f32_32x32x16_bf16 v[2:17], v[208:211], v[142:145], v[2:17]
	s_waitcnt lgkmcnt(0)
	v_mfma_f32_32x32x16_bf16 v[2:17], v[212:215], v[138:141], v[2:17]
	global_load_dwordx4 v[122:125], v[246:247], off offset:2048
	global_load_dwordx4 v[126:129], v[246:247], off offset:2080
	global_load_dwordx4 v[130:133], v[246:247], off offset:2112
	global_load_dwordx4 v[134:137], v[246:247], off offset:2144
	s_cbranch_vccnz .LBB0_64
	v_mul_f32_e32 v138, 0x3e38aa3b, v66
	v_mul_f32_e32 v139, 0x3e38aa3b, v67
	v_max3_f32 v138, v153, v138, v139
	v_mul_f32_e32 v139, 0x3e38aa3b, v68
	v_mul_f32_e32 v140, 0x3e38aa3b, v69
	v_max3_f32 v138, v138, v139, v140
	v_mul_f32_e32 v139, 0x3e38aa3b, v70
	v_mul_f32_e32 v140, 0x3e38aa3b, v71
	v_max3_f32 v138, v138, v139, v140
	v_mul_f32_e32 v139, 0x3e38aa3b, v72
	v_mul_f32_e32 v140, 0x3e38aa3b, v73
	v_max3_f32 v138, v138, v139, v140
	v_mul_f32_e32 v139, 0x3e38aa3b, v74
	v_mul_f32_e32 v140, 0x3e38aa3b, v75
	v_max3_f32 v138, v138, v139, v140
	v_mul_f32_e32 v139, 0x3e38aa3b, v76
	v_mul_f32_e32 v140, 0x3e38aa3b, v77
	v_max3_f32 v138, v138, v139, v140
	v_mul_f32_e32 v139, 0x3e38aa3b, v78
	v_mul_f32_e32 v140, 0x3e38aa3b, v79
	v_max3_f32 v138, v138, v139, v140
	v_mul_f32_e32 v139, 0x3e38aa3b, v80
	v_mul_f32_e32 v140, 0x3e38aa3b, v81
	v_max3_f32 v177, v138, v139, v140
